# baseline (speedup 1.0000x reference)
; __device__ __forceinline__ void ssd_dt_acum(const float* DT, int rb, int L, int h, float a, int lane, float& dt, float& acum) {
;   dt = (lane < L) ? DT[(long)(rb + lane) * 32 + h] : 0.f;
;   float v = dt * a;
; #pragma unroll
;   for (int o = 1; o < 64; o <<= 1) { const float t = bperm(v, lane - o); if (lane >= o) v += t; }
;   acum = v;
; }
; __device__ __forceinline__ void ssd_states_item(KP P, int l, int seq, int c, int g, char* smem) {
;     ...
;   const float a = -__expf(P->a_log[l * 32 + h]);
;   float dt, acum;
;   ssd_dt_acum(DT, rb, L, h, a, lane, dt, acum);
;   const float tot = bperm(acum, 63);
;   const float scale = dt * __expf(tot - acum);
;   if (!isS && lane == 0) CD[(seq * 64 + c) * 32 + h] = __expf(tot);
; #pragma unroll
;   for (int i = 0; i < 8; ++i) {
;     const int tok = i * 8 + (lane >> 3), vec = lane & 7;
;     const float sc = bperm(scale, tok);
;     uint4 v = make_uint4(zz, zz, zz, zz);
;     if (tok < L) {
;       float f[8];
;       unpack8(*(const uint4*)(XBC + (long)(rb + tok) * 3072 + h * 64 + vec * 8), f);
; #pragma unroll
;       for (int q = 0; q < 8; ++q) f[q] *= sc;
;       v = pack8(f);
;     }
;     *(uint4*)(Xs + tok * 72 + vec * 8) = v;
;   }
;   __syncthreads();
.LBB0_829:
	s_or_b64 exec, exec, s[0:1]
	v_lshlrev_b32_e32 v12, 6, v0
	v_lshrrev_b32_e32 v17, 3, v14
	v_lshlrev_b32_e32 v2, 4, v16
	v_ashrrev_i32_e32 v13, 31, v12
	v_readlane_b32 s0, v252, 42
	v_and_b32_e32 v2, 0x70, v2
	v_lshl_add_u64 v[12:13], v[12:13], 1, s[6:7]
	v_or_b32_e32 v11, s0, v17
	v_lshl_add_u64 v[12:13], v[12:13], 0, v[2:3]
	v_mul_u32_u24_e32 v18, 0x1800, v11
	v_mov_b32_e32 v19, v3
	v_lshl_add_u64 v[18:19], v[12:13], 0, v[18:19]
	s_waitcnt vmcnt(0)
	v_mul_f32_e32 v10, 0x3fb8aa3b, v10
	global_load_dwordx4 v[18:21], v[18:19], off
	v_exp_f32_e32 v10, v10
	s_movk_i32 s1, 0x2400
	v_mul_lo_u32 v11, v15, s1
	v_lshlrev_b32_e32 v15, 2, v14
	v_add_u32_e32 v26, 0, v11
	v_add_u32_e32 v11, -4, v15
	v_mul_f32_e64 v23, v9, -v10
	ds_bpermute_b32 v11, v11, v23
	v_mul_u32_u24_e32 v24, 0x90, v17
	v_or_b32_e32 v27, 8, v17
	v_add3_u32 v28, v26, v2, v24
	v_or_b32_e32 v2, s0, v27
	v_cmp_eq_u32_e64 s[6:7], 0, v14
	s_waitcnt lgkmcnt(0)
	v_fma_f32 v10, v9, -v10, v11
	v_mul_u32_u24_e32 v2, 0x1800, v2
	v_cndmask_b32_e64 v23, v10, v23, s[6:7]
	v_lshl_add_u64 v[10:11], v[12:13], 0, v[2:3]
	global_load_dwordx4 v[10:13], v[10:11], off
	v_add_u32_e32 v22, -8, v15
	ds_bpermute_b32 v22, v22, v23
	v_cmp_gt_u32_e32 vcc, 2, v14
	v_add_u32_e32 v2, -16, v15
	v_lshlrev_b64 v[0:1], 13, v[0:1]
	v_or_b32_e32 v90, 16, v84
	s_waitcnt lgkmcnt(0)
	v_add_f32_e32 v22, v23, v22
	v_cndmask_b32_e32 v22, v22, v23, vcc
	ds_bpermute_b32 v2, v2, v22
	v_cmp_gt_u32_e32 vcc, 4, v14
	v_subrev_u32_e32 v23, 32, v15
	v_or_b32_e32 v91, 32, v84
	v_or_b32_e32 v93, 48, v84
	s_waitcnt lgkmcnt(0)
	v_add_f32_e32 v2, v22, v2
	v_cndmask_b32_e32 v2, v2, v22, vcc
	ds_bpermute_b32 v22, v23, v2
	v_cmp_gt_u32_e32 vcc, 8, v14
	v_subrev_u32_e32 v23, 64, v15
	v_add_u32_e32 v15, 0xffffff80, v15
	v_or_b32_e32 v92, 64, v84
	s_waitcnt lgkmcnt(0)
	v_add_f32_e32 v22, v2, v22
	v_cndmask_b32_e32 v2, v22, v2, vcc
	ds_bpermute_b32 v22, v23, v2
	v_cmp_gt_u32_e32 vcc, 32, v14
	v_or_b32_e32 v89, 0x50, v84
	v_or_b32_e32 v88, 0x60, v84
	s_waitcnt lgkmcnt(0)
	v_add_f32_e32 v22, v2, v22
	v_cndmask_b32_e64 v2, v22, v2, s[4:5]
	ds_bpermute_b32 v15, v15, v2
	v_readlane_b32 s4, v251, 13
	v_readlane_b32 s5, v251, 14
	s_lshl_b32 s1, s4, 21
	v_readlane_b32 s4, v252, 46
	s_waitcnt lgkmcnt(0)
	v_add_f32_e32 v15, v2, v15
	v_cndmask_b32_e32 v2, v15, v2, vcc
	v_lshlrev_b32_e32 v15, 2, v17
	v_readlane_b32 s0, v2, 63
	s_or_b32 s26, s1, s4
	v_lshl_add_u64 v[0:1], v[0:1], 0, s[26:27]
	v_sub_f32_e32 v2, s0, v2
	v_mul_f32_e32 v2, 0x3fb8aa3b, v2
	v_exp_f32_e32 v2, v2
	s_waitcnt vmcnt(1)
	v_and_b32_e32 v23, 0xffff0000, v19
	v_mul_f32_e32 v9, v9, v2
	ds_bpermute_b32 v2, v15, v9
	v_and_b32_e32 v22, 0xffff0000, v18
	v_lshlrev_b32_e32 v19, 16, v19
	v_lshlrev_b32_e32 v18, 16, v18
	v_and_b32_e32 v25, 0xffff0000, v21
	v_and_b32_e32 v24, 0xffff0000, v20
	v_lshlrev_b32_e32 v21, 16, v21
	v_lshlrev_b32_e32 v20, 16, v20
	s_waitcnt lgkmcnt(0)
	v_pk_mul_f32 v[22:23], v[2:3], v[22:23] op_sel_hi:[0,1]
	v_pk_mul_f32 v[18:19], v[2:3], v[18:19] op_sel_hi:[0,1]
	v_pk_mul_f32 v[24:25], v[2:3], v[24:25] op_sel_hi:[0,1]
	v_pk_mul_f32 v[20:21], v[2:3], v[20:21] op_sel_hi:[0,1]
	v_and_b32_sdwa v2, v23, v226 dst_sel:DWORD dst_unused:UNUSED_PAD src0_sel:WORD_1 src1_sel:DWORD
	v_and_b32_sdwa v17, v19, v226 dst_sel:DWORD dst_unused:UNUSED_PAD src0_sel:WORD_1 src1_sel:DWORD
	v_add3_u32 v2, v23, v2, s33
	v_and_b32_sdwa v15, v22, v226 dst_sel:DWORD dst_unused:UNUSED_PAD src0_sel:WORD_1 src1_sel:DWORD
	v_and_b32_sdwa v30, v25, v226 dst_sel:DWORD dst_unused:UNUSED_PAD src0_sel:WORD_1 src1_sel:DWORD
	v_add3_u32 v17, v19, v17, s33
	v_and_b32_e32 v2, 0xffff0000, v2
	v_add3_u32 v15, v22, v15, s33
	v_add3_u32 v22, v25, v30, s33
	v_or_b32_sdwa v19, v2, v17 dst_sel:DWORD dst_unused:UNUSED_PAD src0_sel:DWORD src1_sel:WORD_1
	v_and_b32_sdwa v17, v21, v226 dst_sel:DWORD dst_unused:UNUSED_PAD src0_sel:WORD_1 src1_sel:DWORD
	v_and_b32_e32 v2, 0xffff0000, v22
	v_add3_u32 v17, v21, v17, s33
	v_or_b32_sdwa v21, v2, v17 dst_sel:DWORD dst_unused:UNUSED_PAD src0_sel:DWORD src1_sel:WORD_1
	v_lshlrev_b32_e32 v2, 2, v27
	v_and_b32_sdwa v29, v18, v226 dst_sel:DWORD dst_unused:UNUSED_PAD src0_sel:WORD_1 src1_sel:DWORD
	v_and_b32_sdwa v31, v24, v226 dst_sel:DWORD dst_unused:UNUSED_PAD src0_sel:WORD_1 src1_sel:DWORD
	ds_bpermute_b32 v2, v2, v9
	v_add3_u32 v18, v18, v29, s33
	v_add3_u32 v23, v24, v31, s33
	v_and_b32_e32 v15, 0xffff0000, v15
	v_and_b32_sdwa v22, v20, v226 dst_sel:DWORD dst_unused:UNUSED_PAD src0_sel:WORD_1 src1_sel:DWORD
	v_or_b32_sdwa v18, v15, v18 dst_sel:DWORD dst_unused:UNUSED_PAD src0_sel:DWORD src1_sel:WORD_1
	v_and_b32_e32 v15, 0xffff0000, v23
	v_add3_u32 v20, v20, v22, s33
	v_or_b32_sdwa v20, v15, v20 dst_sel:DWORD dst_unused:UNUSED_PAD src0_sel:DWORD src1_sel:WORD_1
	ds_write_b128 v28, v[18:21] offset:17408
	s_waitcnt vmcnt(0)
	v_and_b32_e32 v19, 0xffff0000, v11
	v_and_b32_e32 v18, 0xffff0000, v10
	s_waitcnt lgkmcnt(1)
; __device__ __forceinline__ bf16x8 cat44(s16x4 a, s16x4 b) { return (bf16x8){a[0], a[1], a[2], a[3], b[0], b[1], b[2], b[3]}; }
; __device__ __forceinline__ void ssd_states_item(KP P, int l, int seq, int c, int g, char* smem) {
;     ...
;   f32x4 acc[4][8] = {};
;   const int trr = (lane >> 4) * 8 + ((lane >> 2) & 3), trc = (lane & 3) * 4;
; #pragma unroll
;   for (int ks = 0; ks < 2; ++ks) {
;     bf16x8 af[4];
; #pragma unroll
;     for (int mb = 0; mb < 4; ++mb) {
;       const u16* p0 = Xs + (ks * 32 + trr) * 72 + mb * 16 + trc;
;       af[mb] = cat44(ldtr(p0), ldtr(p0 + 4 * 72));
;     }
; #pragma unroll
;     for (int nb = 0; nb < 8; ++nb) {
;       const u16* p0 = Bs + (ks * 32 + trr) * 136 + nb * 16 + trc;
;       const bf16x8 bf = cat44(ldtr(p0), ldtr(p0 + 4 * 136));
; #pragma unroll
;       for (int mb = 0; mb < 4; ++mb) acc[mb][nb] = __builtin_amdgcn_mfma_f32_16x16x32_bf16(af[mb], bf, acc[mb][nb], 0, 0, 0);
;     }
;   }
;     ...
;   } else {
;     const int bs = seq - 2;
;     const float* h0 = P->st_ssm + ((long)(l * 8 + bs) * 32 + h) * 8192;
;     float* dst = P->out + O_SSMS + ((long)(l * 8 + bs) * 32 + h) * 8192;
;     const float bd = __expf(tot);
; #pragma unroll
;     for (int mb = 0; mb < 4; ++mb)
; #pragma unroll
;       for (int nb = 0; nb < 8; ++nb)
; #pragma unroll
;         for (int j = 0; j < 4; ++j) {
;           const int o = (mb * 16 + (lane >> 4) * 4 + j) * 128 + nb * 16 + (lane & 15);
;           dst[o] = h0[o] * bd + acc[mb][nb][j];
	v_pk_mul_f32 v[18:19], v[2:3], v[18:19] op_sel_hi:[0,1]
	v_lshlrev_b32_e32 v11, 16, v11
	v_lshlrev_b32_e32 v10, 16, v10
	v_pk_mul_f32 v[10:11], v[2:3], v[10:11] op_sel_hi:[0,1]
	v_and_b32_sdwa v15, v18, v226 dst_sel:DWORD dst_unused:UNUSED_PAD src0_sel:WORD_1 src1_sel:DWORD
	v_and_b32_sdwa v9, v19, v226 dst_sel:DWORD dst_unused:UNUSED_PAD src0_sel:WORD_1 src1_sel:DWORD
	v_add3_u32 v15, v18, v15, s33
	v_and_b32_sdwa v18, v10, v226 dst_sel:DWORD dst_unused:UNUSED_PAD src0_sel:WORD_1 src1_sel:DWORD
	v_add3_u32 v9, v19, v9, s33
	v_and_b32_sdwa v17, v11, v226 dst_sel:DWORD dst_unused:UNUSED_PAD src0_sel:WORD_1 src1_sel:DWORD
	v_add3_u32 v10, v10, v18, s33
	v_and_b32_e32 v19, 0xffff0000, v13
	v_and_b32_e32 v18, 0xffff0000, v12
	v_and_b32_e32 v9, 0xffff0000, v9
	v_add3_u32 v11, v11, v17, s33
	v_pk_mul_f32 v[18:19], v[2:3], v[18:19] op_sel_hi:[0,1]
	v_lshlrev_b32_e32 v13, 16, v13
	v_lshlrev_b32_e32 v12, 16, v12
	v_and_b32_e32 v15, 0xffff0000, v15
	v_or_b32_sdwa v11, v9, v11 dst_sel:DWORD dst_unused:UNUSED_PAD src0_sel:DWORD src1_sel:WORD_1
	v_pk_mul_f32 v[12:13], v[2:3], v[12:13] op_sel_hi:[0,1]
	v_and_b32_sdwa v2, v19, v226 dst_sel:DWORD dst_unused:UNUSED_PAD src0_sel:WORD_1 src1_sel:DWORD
	v_and_b32_sdwa v9, v18, v226 dst_sel:DWORD dst_unused:UNUSED_PAD src0_sel:WORD_1 src1_sel:DWORD
	v_or_b32_sdwa v10, v15, v10 dst_sel:DWORD dst_unused:UNUSED_PAD src0_sel:DWORD src1_sel:WORD_1
	v_add3_u32 v2, v19, v2, s33
	v_add3_u32 v9, v18, v9, s33
	v_and_b32_sdwa v15, v13, v226 dst_sel:DWORD dst_unused:UNUSED_PAD src0_sel:WORD_1 src1_sel:DWORD
	v_and_b32_sdwa v17, v12, v226 dst_sel:DWORD dst_unused:UNUSED_PAD src0_sel:WORD_1 src1_sel:DWORD
	v_and_b32_e32 v2, 0xffff0000, v2
	v_and_b32_e32 v9, 0xffff0000, v9
	v_add3_u32 v12, v12, v17, s33
	v_add3_u32 v13, v13, v15, s33
	v_or_b32_sdwa v13, v2, v13 dst_sel:DWORD dst_unused:UNUSED_PAD src0_sel:DWORD src1_sel:WORD_1
	v_or_b32_sdwa v12, v9, v12 dst_sel:DWORD dst_unused:UNUSED_PAD src0_sel:DWORD src1_sel:WORD_1
	ds_write_b128 v28, v[10:13] offset:18560
	v_mov_b32_e32 v9, v8
	v_mov_b32_e32 v10, v8
	v_mov_b32_e32 v11, v8
	ds_write_b128 v28, v[8:11] offset:19712
	ds_write_b128 v28, v[8:11] offset:20864
	ds_write_b128 v28, v[8:11] offset:22016
	ds_write_b128 v28, v[8:11] offset:23168
	ds_write_b128 v28, v[8:11] offset:24320
	ds_write_b128 v28, v[8:11] offset:25472
	s_waitcnt lgkmcnt(0)
	s_barrier
	s_load_dwordx2 s[4:5], s[8:9], 0x20
	v_lshrrev_b32_e32 v8, 4, v14
	v_lshlrev_b32_e32 v86, 9, v8
	v_lshlrev_b64 v[18:19], 2, v[0:1]
	v_or_b32_e32 v2, v86, v84
	s_waitcnt lgkmcnt(0)
	v_lshl_add_u64 v[0:1], s[4:5], 0, v[18:19]
	v_and_b32_e32 v216, 63, v188
	v_lshlrev_b32_e32 v216, 9, v216
	v_mov_b32_e32 v217, 0
	v_lshl_add_u64 v[218:219], v[0:1], 0, v[216:217]
	global_load_dword v220, v[218:219], off
	global_load_dword v220, v[218:219], off offset:128
	global_load_dword v220, v[218:219], off offset:256
	global_load_dword v220, v[218:219], off offset:384
	v_lshlrev_b32_e32 v2, 2, v2
	v_lshl_add_u64 v[12:13], v[0:1], 0, v[2:3]
	global_load_dword v20, v[12:13], off
	v_bfe_u32 v9, v16, 2, 2
	v_lshl_or_b32 v8, v8, 3, v9
	v_lshlrev_b32_e32 v9, 3, v16
	v_and_b32_e32 v9, 24, v9
	v_mul_u32_u24_e32 v10, 0x90, v8
	v_add3_u32 v94, v26, v9, v10
	ds_read_b64_tr_b16 v[72:73], v94 offset:17408
	ds_read_b64_tr_b16 v[74:75], v94 offset:17984
	v_mul_u32_u24_e32 v8, 0x110, v8
	v_add3_u32 v87, 0, v9, v8
	ds_read_b64_tr_b16 v[70:71], v87 offset:1088
	ds_read_b64_tr_b16 v[68:69], v87
	ds_read_b64_tr_b16 v[76:77], v94 offset:22016
	ds_read_b64_tr_b16 v[78:79], v94 offset:22592
	ds_read_b64_tr_b16 v[8:9], v87 offset:8704
	ds_read_b64_tr_b16 v[10:11], v87 offset:9792
	s_waitcnt lgkmcnt(4)
	v_mfma_f32_16x16x32_bf16 v[14:17], v[72:75], v[68:71], 0
	s_load_dwordx2 s[4:5], s[8:9], 0xd0
	v_mul_f32_e32 v21, s0, v233
	v_exp_f32_e32 v85, v21
	s_waitcnt lgkmcnt(0)
	v_mfma_f32_16x16x32_bf16 v[14:17], v[76:79], v[8:11], v[14:17]
	s_mov_b64 s[0:1], 0x6900000
	v_lshl_add_u64 v[18:19], s[4:5], 0, v[18:19]
	v_lshl_add_u64 v[80:81], v[18:19], 0, s[0:1]
	v_lshl_add_u64 v[82:83], v[80:81], 0, v[2:3]
	v_or_b32_e32 v104, 0x880, v86
	v_or_b32_e32 v100, v104, v84
	v_or_b32_e32 v105, 0x900, v86
	v_or_b32_e32 v106, 0x980, v86
	v_or_b32_e32 v108, v104, v90
	v_or_b32_e32 v109, 0x1180, v86
	global_load_dword v208, v[12:13], off offset:512
	global_load_dword v209, v[12:13], off offset:1024
	global_load_dword v210, v[12:13], off offset:1536
	s_waitcnt vmcnt(0)
	v_fma_f32 v14, v85, v20, v14
	global_store_dword v[82:83], v14, off
	v_mov_b32_e32 v2, v208
	v_fma_f32 v2, v85, v2, v15
	global_store_dword v[82:83], v2, off offset:512
	v_mov_b32_e32 v2, v209
	v_fma_f32 v2, v85, v2, v16
	global_store_dword v[82:83], v2, off offset:1024
	v_mov_b32_e32 v2, v210
	v_fmac_f32_e32 v17, v85, v2
	global_store_dword v[82:83], v17, off offset:1536
	global_load_dword v20, v[12:13], off offset:64
	ds_read_b64_tr_b16 v[40:41], v87 offset:32
	ds_read_b64_tr_b16 v[42:43], v87 offset:1120
	ds_read_b64_tr_b16 v[32:33], v87 offset:8736
	ds_read_b64_tr_b16 v[34:35], v87 offset:9824
	s_waitcnt lgkmcnt(2)
	v_mfma_f32_16x16x32_bf16 v[14:17], v[72:75], v[40:43], 0
	v_or_b32_e32 v2, v86, v90
	v_lshlrev_b32_e32 v2, 2, v2
	v_lshl_add_u64 v[18:19], v[0:1], 0, v[2:3]
	s_waitcnt lgkmcnt(0)
	v_mfma_f32_16x16x32_bf16 v[14:17], v[76:79], v[32:35], v[14:17]
	global_load_dword v208, v[18:19], off offset:512
	global_load_dword v209, v[18:19], off offset:1024
	global_load_dword v210, v[18:19], off offset:1536
	s_waitcnt vmcnt(0)
; __device__ __forceinline__ bf16x8 cat44(s16x4 a, s16x4 b) { return (bf16x8){a[0], a[1], a[2], a[3], b[0], b[1], b[2], b[3]}; }
; __device__ __forceinline__ void ssd_states_item(KP P, int l, int seq, int c, int g, char* smem) {
;     ...
;     for (int nb = 0; nb < 8; ++nb) {
;       const u16* p0 = Bs + (ks * 32 + trr) * 136 + nb * 16 + trc;
;       const bf16x8 bf = cat44(ldtr(p0), ldtr(p0 + 4 * 136));
; #pragma unroll
;       for (int mb = 0; mb < 4; ++mb) acc[mb][nb] = __builtin_amdgcn_mfma_f32_16x16x32_bf16(af[mb], bf, acc[mb][nb], 0, 0, 0);
;     ...
;     const float bd = __expf(tot);
; #pragma unroll
;     for (int mb = 0; mb < 4; ++mb)
; #pragma unroll
;       for (int nb = 0; nb < 8; ++nb)
; #pragma unroll
;         for (int j = 0; j < 4; ++j) {
;           const int o = (mb * 16 + (lane >> 4) * 4 + j) * 128 + nb * 16 + (lane & 15);
;           dst[o] = h0[o] * bd + acc[mb][nb][j];
	s_nop 6
	v_fma_f32 v14, v85, v20, v14
	global_store_dword v[82:83], v14, off offset:64
	v_mov_b32_e32 v14, v208
	v_lshl_add_u64 v[20:21], v[80:81], 0, v[2:3]
	v_fma_f32 v2, v85, v14, v15
	global_store_dword v[20:21], v2, off offset:512
	v_mov_b32_e32 v2, v209
	v_fma_f32 v2, v85, v2, v16
	global_store_dword v[20:21], v2, off offset:1024
	v_mov_b32_e32 v2, v210
	v_fmac_f32_e32 v17, v85, v2
	global_store_dword v[20:21], v17, off offset:1536
	global_load_dword v20, v[12:13], off offset:128
	ds_read_b64_tr_b16 v[52:53], v87 offset:64
	ds_read_b64_tr_b16 v[54:55], v87 offset:1152
	ds_read_b64_tr_b16 v[44:45], v87 offset:8768
	ds_read_b64_tr_b16 v[46:47], v87 offset:9856
	s_waitcnt lgkmcnt(2)
	v_mfma_f32_16x16x32_bf16 v[14:17], v[72:75], v[52:55], 0
	v_or_b32_e32 v2, v86, v91
	v_lshlrev_b32_e32 v2, 2, v2
	v_lshl_add_u64 v[18:19], v[0:1], 0, v[2:3]
	s_waitcnt lgkmcnt(0)
	v_mfma_f32_16x16x32_bf16 v[14:17], v[76:79], v[44:47], v[14:17]
	global_load_dword v208, v[18:19], off offset:512
	global_load_dword v209, v[18:19], off offset:1024
	global_load_dword v210, v[18:19], off offset:1536
	s_waitcnt vmcnt(0)
	s_nop 6
	v_fma_f32 v14, v85, v20, v14
	global_store_dword v[82:83], v14, off offset:128
	v_mov_b32_e32 v14, v208
	v_lshl_add_u64 v[20:21], v[80:81], 0, v[2:3]
	v_fma_f32 v2, v85, v14, v15
	global_store_dword v[20:21], v2, off offset:512
	v_mov_b32_e32 v2, v209
	v_fma_f32 v2, v85, v2, v16
	global_store_dword v[20:21], v2, off offset:1024
	v_mov_b32_e32 v2, v210
	v_fmac_f32_e32 v17, v85, v2
	global_store_dword v[20:21], v17, off offset:1536
	global_load_dword v20, v[12:13], off offset:192
	ds_read_b64_tr_b16 v[64:65], v87 offset:96
	ds_read_b64_tr_b16 v[66:67], v87 offset:1184
	ds_read_b64_tr_b16 v[60:61], v87 offset:8800
	ds_read_b64_tr_b16 v[62:63], v87 offset:9888
	s_waitcnt lgkmcnt(2)
	v_mfma_f32_16x16x32_bf16 v[14:17], v[72:75], v[64:67], 0
	v_or_b32_e32 v2, v86, v93
	v_lshlrev_b32_e32 v2, 2, v2
	v_lshl_add_u64 v[18:19], v[0:1], 0, v[2:3]
	s_waitcnt lgkmcnt(0)
	v_mfma_f32_16x16x32_bf16 v[14:17], v[76:79], v[60:63], v[14:17]
	global_load_dword v208, v[18:19], off offset:512
	global_load_dword v209, v[18:19], off offset:1024
	global_load_dword v210, v[18:19], off offset:1536
	s_waitcnt vmcnt(0)
	s_nop 6
	v_fma_f32 v14, v85, v20, v14
	global_store_dword v[82:83], v14, off offset:192
	v_mov_b32_e32 v14, v208
	v_lshl_add_u64 v[20:21], v[80:81], 0, v[2:3]
	v_fma_f32 v2, v85, v14, v15
	global_store_dword v[20:21], v2, off offset:512
	v_mov_b32_e32 v2, v209
	v_fma_f32 v2, v85, v2, v16
	global_store_dword v[20:21], v2, off offset:1024
	v_mov_b32_e32 v2, v210
	v_fmac_f32_e32 v17, v85, v2
	global_store_dword v[20:21], v17, off offset:1536
	global_load_dword v20, v[12:13], off offset:256
	ds_read_b64_tr_b16 v[56:57], v87 offset:128
	ds_read_b64_tr_b16 v[58:59], v87 offset:1216
	ds_read_b64_tr_b16 v[48:49], v87 offset:8832
	ds_read_b64_tr_b16 v[50:51], v87 offset:9920
	s_waitcnt lgkmcnt(2)
	v_mfma_f32_16x16x32_bf16 v[14:17], v[72:75], v[56:59], 0
	v_or_b32_e32 v2, v86, v92
	v_lshlrev_b32_e32 v2, 2, v2
	v_lshl_add_u64 v[18:19], v[0:1], 0, v[2:3]
	s_waitcnt lgkmcnt(0)
	v_mfma_f32_16x16x32_bf16 v[14:17], v[76:79], v[48:51], v[14:17]
	global_load_dword v208, v[18:19], off offset:512
	global_load_dword v209, v[18:19], off offset:1024
	global_load_dword v210, v[18:19], off offset:1536
	s_waitcnt vmcnt(0)
	s_nop 6
	v_fma_f32 v14, v85, v20, v14
	global_store_dword v[82:83], v14, off offset:256
	v_mov_b32_e32 v14, v208
	v_lshl_add_u64 v[20:21], v[80:81], 0, v[2:3]
	v_fma_f32 v2, v85, v14, v15
	global_store_dword v[20:21], v2, off offset:512
	v_mov_b32_e32 v2, v209
	v_fma_f32 v2, v85, v2, v16
	global_store_dword v[20:21], v2, off offset:1024
	v_mov_b32_e32 v2, v210
	v_fmac_f32_e32 v17, v85, v2
	global_store_dword v[20:21], v17, off offset:1536
	global_load_dword v20, v[12:13], off offset:320
	ds_read_b64_tr_b16 v[36:37], v87 offset:160
	ds_read_b64_tr_b16 v[38:39], v87 offset:1248
	ds_read_b64_tr_b16 v[28:29], v87 offset:8864
	ds_read_b64_tr_b16 v[30:31], v87 offset:9952
	s_waitcnt lgkmcnt(2)
	v_mfma_f32_16x16x32_bf16 v[14:17], v[72:75], v[36:39], 0
	v_or_b32_e32 v2, v86, v89
	v_lshlrev_b32_e32 v2, 2, v2
	v_lshl_add_u64 v[18:19], v[0:1], 0, v[2:3]
	s_waitcnt lgkmcnt(0)
	v_mfma_f32_16x16x32_bf16 v[14:17], v[76:79], v[28:31], v[14:17]
	global_load_dword v208, v[18:19], off offset:512
	global_load_dword v209, v[18:19], off offset:1024
	global_load_dword v210, v[18:19], off offset:1536
	s_waitcnt vmcnt(0)
	s_nop 6
	v_fma_f32 v14, v85, v20, v14
	global_store_dword v[82:83], v14, off offset:320
	v_mov_b32_e32 v14, v208
	v_lshl_add_u64 v[20:21], v[80:81], 0, v[2:3]
	v_fma_f32 v2, v85, v14, v15
	global_store_dword v[20:21], v2, off offset:512
	v_mov_b32_e32 v2, v209
	v_fma_f32 v2, v85, v2, v16
	global_store_dword v[20:21], v2, off offset:1024
	v_mov_b32_e32 v2, v210
	v_fmac_f32_e32 v17, v85, v2
	global_store_dword v[20:21], v17, off offset:1536
	global_load_dword v95, v[12:13], off offset:384
	ds_read_b64_tr_b16 v[24:25], v87 offset:192
	ds_read_b64_tr_b16 v[26:27], v87 offset:1280
	ds_read_b64_tr_b16 v[20:21], v87 offset:8896
	ds_read_b64_tr_b16 v[22:23], v87 offset:9984
	s_waitcnt lgkmcnt(2)
	v_mfma_f32_16x16x32_bf16 v[14:17], v[72:75], v[24:27], 0
	v_or_b32_e32 v2, v86, v88
	v_lshlrev_b32_e32 v2, 2, v2
	v_lshl_add_u64 v[18:19], v[0:1], 0, v[2:3]
	s_waitcnt lgkmcnt(0)
	v_mfma_f32_16x16x32_bf16 v[14:17], v[76:79], v[20:23], v[14:17]
	v_lshl_add_u64 v[96:97], v[80:81], 0, v[2:3]
	global_load_dword v208, v[18:19], off offset:512
	global_load_dword v209, v[18:19], off offset:1024
	global_load_dword v210, v[18:19], off offset:1536
	s_waitcnt vmcnt(0)
; __device__ __forceinline__ bf16x8 cat44(s16x4 a, s16x4 b) { return (bf16x8){a[0], a[1], a[2], a[3], b[0], b[1], b[2], b[3]}; }
; __device__ __forceinline__ void ssd_states_item(KP P, int l, int seq, int c, int g, char* smem) {
;     ...
;     for (int nb = 0; nb < 8; ++nb) {
;       const u16* p0 = Bs + (ks * 32 + trr) * 136 + nb * 16 + trc;
;       const bf16x8 bf = cat44(ldtr(p0), ldtr(p0 + 4 * 136));
; #pragma unroll
;       for (int mb = 0; mb < 4; ++mb) acc[mb][nb] = __builtin_amdgcn_mfma_f32_16x16x32_bf16(af[mb], bf, acc[mb][nb], 0, 0, 0);
;     ...
;     const float bd = __expf(tot);
; #pragma unroll
;     for (int mb = 0; mb < 4; ++mb)
; #pragma unroll
;       for (int nb = 0; nb < 8; ++nb)
; #pragma unroll
;         for (int j = 0; j < 4; ++j) {
;           const int o = (mb * 16 + (lane >> 4) * 4 + j) * 128 + nb * 16 + (lane & 15);
;           dst[o] = h0[o] * bd + acc[mb][nb][j];
	s_nop 5
	v_fma_f32 v14, v85, v95, v14
	global_store_dword v[82:83], v14, off offset:384
	v_mov_b32_e32 v14, v208
	v_fma_f32 v2, v85, v14, v15
	global_store_dword v[96:97], v2, off offset:512
	v_mov_b32_e32 v2, v209
	v_fma_f32 v2, v85, v2, v16
	global_store_dword v[96:97], v2, off offset:1024
	v_mov_b32_e32 v2, v210
	v_fmac_f32_e32 v17, v85, v2
	global_load_dword v95, v[12:13], off offset:448
	global_store_dword v[96:97], v17, off offset:1536
	ds_read_b64_tr_b16 v[16:17], v87 offset:224
	ds_read_b64_tr_b16 v[18:19], v87 offset:1312
	ds_read_b64_tr_b16 v[12:13], v87 offset:8928
	ds_read_b64_tr_b16 v[14:15], v87 offset:10016
	s_waitcnt lgkmcnt(2)
	v_mfma_f32_16x16x32_bf16 v[72:75], v[72:75], v[16:19], 0
	v_or_b32_e32 v87, 0x70, v84
	v_or_b32_e32 v2, v86, v87
	v_lshlrev_b32_e32 v2, 2, v2
	s_waitcnt lgkmcnt(0)
	v_mfma_f32_16x16x32_bf16 v[72:75], v[76:79], v[12:15], v[72:75]
	v_lshl_add_u64 v[76:77], v[0:1], 0, v[2:3]
	v_lshl_add_u64 v[78:79], v[80:81], 0, v[2:3]
	s_waitcnt vmcnt(1)
	s_nop 4
	v_fma_f32 v72, v85, v95, v72
	global_load_dword v72, v[76:77], off offset:512
	global_store_dword v[82:83], v72, off offset:448
	v_or_b32_e32 v95, 0x800, v86
	s_waitcnt vmcnt(1)
	v_fma_f32 v2, v85, v72, v73
	global_load_dword v2, v[76:77], off offset:1024
	global_store_dword v[78:79], v2, off offset:512
	s_waitcnt vmcnt(1)
	v_fma_f32 v2, v85, v2, v74
	global_load_dword v74, v[76:77], off offset:1536
	global_store_dword v[78:79], v2, off offset:1024
	v_or_b32_e32 v2, v95, v84
	v_lshlrev_b32_e32 v2, 2, v2
	v_lshl_add_u64 v[72:73], v[0:1], 0, v[2:3]
	v_lshl_add_u64 v[82:83], v[80:81], 0, v[2:3]
	v_lshlrev_b32_e32 v2, 2, v100
	v_lshl_add_u64 v[100:101], v[0:1], 0, v[2:3]
	s_waitcnt vmcnt(1)
	v_fmac_f32_e32 v75, v85, v74
	global_load_dword v102, v[72:73], off
	global_store_dword v[78:79], v75, off offset:1536
	ds_read_b64_tr_b16 v[72:73], v94 offset:17440
	ds_read_b64_tr_b16 v[74:75], v94 offset:18016
	ds_read_b64_tr_b16 v[76:77], v94 offset:22048
	ds_read_b64_tr_b16 v[78:79], v94 offset:22624
	s_waitcnt lgkmcnt(2)
	v_mfma_f32_16x16x32_bf16 v[96:99], v[72:75], v[68:71], 0
	s_waitcnt lgkmcnt(0)
	v_mfma_f32_16x16x32_bf16 v[96:99], v[76:79], v[8:11], v[96:99]
	s_waitcnt vmcnt(1)
	s_nop 6
	v_fma_f32 v96, v85, v102, v96
	global_load_dword v96, v[100:101], off
	global_store_dword v[82:83], v96, off
	v_or_b32_e32 v100, v105, v84
	v_lshl_add_u64 v[82:83], v[80:81], 0, v[2:3]
	v_lshlrev_b32_e32 v2, 2, v100
	v_lshl_add_u64 v[100:101], v[0:1], 0, v[2:3]
	s_waitcnt vmcnt(1)
	v_fma_f32 v96, v85, v96, v97
	global_load_dword v100, v[100:101], off
	global_store_dword v[82:83], v96, off
	v_or_b32_e32 v96, v106, v84
	v_lshl_add_u64 v[82:83], v[80:81], 0, v[2:3]
	v_lshlrev_b32_e32 v2, 2, v96
	v_lshl_add_u64 v[96:97], v[0:1], 0, v[2:3]
	s_waitcnt vmcnt(1)
	v_fma_f32 v98, v85, v100, v98
	global_load_dword v98, v[96:97], off
	global_store_dword v[82:83], v98, off
	v_or_b32_e32 v96, v95, v90
	v_lshl_add_u64 v[82:83], v[80:81], 0, v[2:3]
	v_lshlrev_b32_e32 v2, 2, v96
	v_lshl_add_u64 v[96:97], v[0:1], 0, v[2:3]
	v_mfma_f32_16x16x32_bf16 v[100:103], v[72:75], v[40:43], 0
	s_waitcnt vmcnt(1)
	v_fmac_f32_e32 v99, v85, v98
	global_load_dword v107, v[96:97], off
	global_store_dword v[82:83], v99, off
	v_mfma_f32_16x16x32_bf16 v[96:99], v[76:79], v[32:35], v[100:103]
	v_lshl_add_u64 v[82:83], v[80:81], 0, v[2:3]
	v_lshlrev_b32_e32 v2, 2, v108
	v_or_b32_e32 v108, v104, v91
	v_lshl_add_u64 v[100:101], v[0:1], 0, v[2:3]
	s_waitcnt vmcnt(1)
	s_nop 2
	v_fma_f32 v96, v85, v107, v96
	global_load_dword v96, v[100:101], off
	global_store_dword v[82:83], v96, off
	v_or_b32_e32 v100, v105, v90
	v_lshl_add_u64 v[82:83], v[80:81], 0, v[2:3]
	v_lshlrev_b32_e32 v2, 2, v100
	v_lshl_add_u64 v[100:101], v[0:1], 0, v[2:3]
	s_waitcnt vmcnt(1)
	v_fma_f32 v96, v85, v96, v97
	global_load_dword v100, v[100:101], off
	global_store_dword v[82:83], v96, off
	v_or_b32_e32 v96, v106, v90
	v_lshl_add_u64 v[82:83], v[80:81], 0, v[2:3]
	v_lshlrev_b32_e32 v2, 2, v96
	v_lshl_add_u64 v[96:97], v[0:1], 0, v[2:3]
	s_waitcnt vmcnt(1)
	v_fma_f32 v98, v85, v100, v98
	global_load_dword v98, v[96:97], off
	global_store_dword v[82:83], v98, off
	v_or_b32_e32 v96, v95, v91
	v_lshl_add_u64 v[82:83], v[80:81], 0, v[2:3]
	v_lshlrev_b32_e32 v2, 2, v96
	v_lshl_add_u64 v[96:97], v[0:1], 0, v[2:3]
	v_mfma_f32_16x16x32_bf16 v[100:103], v[72:75], v[52:55], 0
	s_waitcnt vmcnt(1)
	v_fmac_f32_e32 v99, v85, v98
	global_load_dword v107, v[96:97], off
	global_store_dword v[82:83], v99, off
	v_mfma_f32_16x16x32_bf16 v[96:99], v[76:79], v[44:47], v[100:103]
	v_lshl_add_u64 v[82:83], v[80:81], 0, v[2:3]
	v_lshlrev_b32_e32 v2, 2, v108
	v_or_b32_e32 v108, v104, v93
	v_lshl_add_u64 v[100:101], v[0:1], 0, v[2:3]
	s_waitcnt vmcnt(1)
	s_nop 2
	v_fma_f32 v96, v85, v107, v96
	global_load_dword v96, v[100:101], off
	global_store_dword v[82:83], v96, off
	v_or_b32_e32 v100, v105, v91
	v_lshl_add_u64 v[82:83], v[80:81], 0, v[2:3]
	v_lshlrev_b32_e32 v2, 2, v100
	v_lshl_add_u64 v[100:101], v[0:1], 0, v[2:3]
	s_waitcnt vmcnt(1)
	v_fma_f32 v96, v85, v96, v97
	global_load_dword v100, v[100:101], off
	global_store_dword v[82:83], v96, off
	v_or_b32_e32 v96, v106, v91
	v_lshl_add_u64 v[82:83], v[80:81], 0, v[2:3]
	v_lshlrev_b32_e32 v2, 2, v96
	v_lshl_add_u64 v[96:97], v[0:1], 0, v[2:3]
	s_waitcnt vmcnt(1)
	v_fma_f32 v98, v85, v100, v98
	global_load_dword v98, v[96:97], off
	global_store_dword v[82:83], v98, off
	v_or_b32_e32 v96, v95, v93
	v_lshl_add_u64 v[82:83], v[80:81], 0, v[2:3]
	v_lshlrev_b32_e32 v2, 2, v96
	v_lshl_add_u64 v[96:97], v[0:1], 0, v[2:3]
	v_mfma_f32_16x16x32_bf16 v[100:103], v[72:75], v[64:67], 0
	s_waitcnt vmcnt(1)
; __device__ __forceinline__ bf16x8 cat44(s16x4 a, s16x4 b) { return (bf16x8){a[0], a[1], a[2], a[3], b[0], b[1], b[2], b[3]}; }
; __device__ __forceinline__ void ssd_states_item(KP P, int l, int seq, int c, int g, char* smem) {
;     ...
;     for (int nb = 0; nb < 8; ++nb) {
;       const u16* p0 = Bs + (ks * 32 + trr) * 136 + nb * 16 + trc;
;       const bf16x8 bf = cat44(ldtr(p0), ldtr(p0 + 4 * 136));
; #pragma unroll
;       for (int mb = 0; mb < 4; ++mb) acc[mb][nb] = __builtin_amdgcn_mfma_f32_16x16x32_bf16(af[mb], bf, acc[mb][nb], 0, 0, 0);
;     ...
;     const float bd = __expf(tot);
; #pragma unroll
;     for (int mb = 0; mb < 4; ++mb)
; #pragma unroll
;       for (int nb = 0; nb < 8; ++nb)
; #pragma unroll
;         for (int j = 0; j < 4; ++j) {
;           const int o = (mb * 16 + (lane >> 4) * 4 + j) * 128 + nb * 16 + (lane & 15);
;           dst[o] = h0[o] * bd + acc[mb][nb][j];
	v_fmac_f32_e32 v99, v85, v98
	global_load_dword v107, v[96:97], off
	global_store_dword v[82:83], v99, off
	v_mfma_f32_16x16x32_bf16 v[96:99], v[76:79], v[60:63], v[100:103]
	v_lshl_add_u64 v[82:83], v[80:81], 0, v[2:3]
	v_lshlrev_b32_e32 v2, 2, v108
	v_or_b32_e32 v108, v104, v92
	v_lshl_add_u64 v[100:101], v[0:1], 0, v[2:3]
	s_waitcnt vmcnt(1)
	s_nop 2
	v_fma_f32 v96, v85, v107, v96
	global_load_dword v96, v[100:101], off
	global_store_dword v[82:83], v96, off
	v_or_b32_e32 v100, v105, v93
	v_lshl_add_u64 v[82:83], v[80:81], 0, v[2:3]
	v_lshlrev_b32_e32 v2, 2, v100
	v_lshl_add_u64 v[100:101], v[0:1], 0, v[2:3]
	s_waitcnt vmcnt(1)
	v_fma_f32 v96, v85, v96, v97
	global_load_dword v100, v[100:101], off
	global_store_dword v[82:83], v96, off
	v_or_b32_e32 v96, v106, v93
	v_lshl_add_u64 v[82:83], v[80:81], 0, v[2:3]
	v_lshlrev_b32_e32 v2, 2, v96
	v_lshl_add_u64 v[96:97], v[0:1], 0, v[2:3]
	s_waitcnt vmcnt(1)
	v_fma_f32 v98, v85, v100, v98
	global_load_dword v98, v[96:97], off
	global_store_dword v[82:83], v98, off
	v_or_b32_e32 v96, v95, v92
	v_lshl_add_u64 v[82:83], v[80:81], 0, v[2:3]
	v_lshlrev_b32_e32 v2, 2, v96
	v_lshl_add_u64 v[96:97], v[0:1], 0, v[2:3]
	v_mfma_f32_16x16x32_bf16 v[100:103], v[72:75], v[56:59], 0
	s_waitcnt vmcnt(1)
	v_fmac_f32_e32 v99, v85, v98
	global_load_dword v107, v[96:97], off
	global_store_dword v[82:83], v99, off
	v_mfma_f32_16x16x32_bf16 v[96:99], v[76:79], v[48:51], v[100:103]
	v_lshl_add_u64 v[82:83], v[80:81], 0, v[2:3]
	v_lshlrev_b32_e32 v2, 2, v108
	v_or_b32_e32 v108, v104, v89
	v_lshl_add_u64 v[100:101], v[0:1], 0, v[2:3]
	s_waitcnt vmcnt(1)
	s_nop 2
	v_fma_f32 v96, v85, v107, v96
	global_load_dword v96, v[100:101], off
	global_store_dword v[82:83], v96, off
	v_or_b32_e32 v100, v105, v92
	v_lshl_add_u64 v[82:83], v[80:81], 0, v[2:3]
	v_lshlrev_b32_e32 v2, 2, v100
	v_lshl_add_u64 v[100:101], v[0:1], 0, v[2:3]
	s_waitcnt vmcnt(1)
	v_fma_f32 v96, v85, v96, v97
	global_load_dword v100, v[100:101], off
	global_store_dword v[82:83], v96, off
	v_or_b32_e32 v96, v106, v92
	v_lshl_add_u64 v[82:83], v[80:81], 0, v[2:3]
	v_lshlrev_b32_e32 v2, 2, v96
	v_lshl_add_u64 v[96:97], v[0:1], 0, v[2:3]
	s_waitcnt vmcnt(1)
	v_fma_f32 v98, v85, v100, v98
	global_load_dword v98, v[96:97], off
	global_store_dword v[82:83], v98, off
	v_or_b32_e32 v96, v95, v89
	v_lshl_add_u64 v[82:83], v[80:81], 0, v[2:3]
	v_lshlrev_b32_e32 v2, 2, v96
	v_lshl_add_u64 v[96:97], v[0:1], 0, v[2:3]
	v_mfma_f32_16x16x32_bf16 v[100:103], v[72:75], v[36:39], 0
	s_waitcnt vmcnt(1)
	v_fmac_f32_e32 v99, v85, v98
	global_load_dword v107, v[96:97], off
	global_store_dword v[82:83], v99, off
	v_mfma_f32_16x16x32_bf16 v[96:99], v[76:79], v[28:31], v[100:103]
	v_lshl_add_u64 v[82:83], v[80:81], 0, v[2:3]
	v_lshlrev_b32_e32 v2, 2, v108
	v_or_b32_e32 v108, v104, v88
	v_lshl_add_u64 v[100:101], v[0:1], 0, v[2:3]
	s_waitcnt vmcnt(1)
	s_nop 2
	v_fma_f32 v96, v85, v107, v96
	global_load_dword v96, v[100:101], off
	global_store_dword v[82:83], v96, off
	v_or_b32_e32 v100, v105, v89
	v_lshl_add_u64 v[82:83], v[80:81], 0, v[2:3]
	v_lshlrev_b32_e32 v2, 2, v100
	v_lshl_add_u64 v[100:101], v[0:1], 0, v[2:3]
	s_waitcnt vmcnt(1)
	v_fma_f32 v96, v85, v96, v97
	global_load_dword v100, v[100:101], off
	global_store_dword v[82:83], v96, off
	v_or_b32_e32 v96, v106, v89
	v_lshl_add_u64 v[82:83], v[80:81], 0, v[2:3]
	v_lshlrev_b32_e32 v2, 2, v96
	v_lshl_add_u64 v[96:97], v[0:1], 0, v[2:3]
	s_waitcnt vmcnt(1)
	v_fma_f32 v98, v85, v100, v98
	global_load_dword v98, v[96:97], off
	global_store_dword v[82:83], v98, off
	v_or_b32_e32 v96, v95, v88
	v_lshl_add_u64 v[82:83], v[80:81], 0, v[2:3]
	v_lshlrev_b32_e32 v2, 2, v96
	v_lshl_add_u64 v[96:97], v[0:1], 0, v[2:3]
	v_mfma_f32_16x16x32_bf16 v[100:103], v[72:75], v[24:27], 0
	v_or_b32_e32 v95, v95, v87
	s_waitcnt vmcnt(1)
	v_fmac_f32_e32 v99, v85, v98
	global_load_dword v107, v[96:97], off
	global_store_dword v[82:83], v99, off
	v_mfma_f32_16x16x32_bf16 v[96:99], v[76:79], v[20:23], v[100:103]
	v_lshl_add_u64 v[82:83], v[80:81], 0, v[2:3]
	v_lshlrev_b32_e32 v2, 2, v108
	v_or_b32_e32 v108, 0x1100, v86
	v_lshl_add_u64 v[100:101], v[0:1], 0, v[2:3]
	v_mfma_f32_16x16x32_bf16 v[72:75], v[72:75], v[16:19], 0
	s_waitcnt vmcnt(1)
	s_nop 1
	v_fma_f32 v96, v85, v107, v96
	global_load_dword v96, v[100:101], off
	global_store_dword v[82:83], v96, off
	v_or_b32_e32 v100, v105, v88
	v_lshl_add_u64 v[82:83], v[80:81], 0, v[2:3]
	v_lshlrev_b32_e32 v2, 2, v100
	v_lshl_add_u64 v[100:101], v[0:1], 0, v[2:3]
	v_mfma_f32_16x16x32_bf16 v[72:75], v[76:79], v[12:15], v[72:75]
	s_waitcnt vmcnt(1)
	v_fma_f32 v96, v85, v96, v97
	global_load_dword v100, v[100:101], off
	global_store_dword v[82:83], v96, off
	v_or_b32_e32 v96, v106, v88
	v_lshl_add_u64 v[82:83], v[80:81], 0, v[2:3]
	v_lshlrev_b32_e32 v2, 2, v96
	v_lshl_add_u64 v[96:97], v[0:1], 0, v[2:3]
	s_waitcnt vmcnt(1)
	v_fma_f32 v98, v85, v100, v98
	global_load_dword v98, v[96:97], off
	global_store_dword v[82:83], v98, off
	v_lshl_add_u64 v[82:83], v[80:81], 0, v[2:3]
	v_lshlrev_b32_e32 v2, 2, v95
	v_lshl_add_u64 v[96:97], v[0:1], 0, v[2:3]
	v_lshl_add_u64 v[76:77], v[80:81], 0, v[2:3]
	v_or_b32_e32 v95, 0x1080, v86
	s_waitcnt vmcnt(1)
	v_fmac_f32_e32 v99, v85, v98
	global_store_dword v[82:83], v99, off
	global_load_dword v82, v[96:97], off
	v_or_b32_e32 v83, v104, v87
	v_lshlrev_b32_e32 v2, 2, v83
	v_lshl_add_u64 v[78:79], v[0:1], 0, v[2:3]
	s_waitcnt vmcnt(0)
	v_fma_f32 v72, v85, v82, v72
	global_load_dword v72, v[78:79], off
	global_store_dword v[76:77], v72, off
	v_or_b32_e32 v78, v105, v87
	v_lshl_add_u64 v[76:77], v[80:81], 0, v[2:3]
	v_lshlrev_b32_e32 v2, 2, v78
	v_lshl_add_u64 v[78:79], v[0:1], 0, v[2:3]
	v_or_b32_e32 v82, v95, v84
	s_waitcnt vmcnt(1)
; __device__ __forceinline__ bf16x8 cat44(s16x4 a, s16x4 b) { return (bf16x8){a[0], a[1], a[2], a[3], b[0], b[1], b[2], b[3]}; }
; __device__ __forceinline__ void ssd_states_item(KP P, int l, int seq, int c, int g, char* smem) {
;     ...
;     for (int nb = 0; nb < 8; ++nb) {
;       const u16* p0 = Bs + (ks * 32 + trr) * 136 + nb * 16 + trc;
;       const bf16x8 bf = cat44(ldtr(p0), ldtr(p0 + 4 * 136));
; #pragma unroll
;       for (int mb = 0; mb < 4; ++mb) acc[mb][nb] = __builtin_amdgcn_mfma_f32_16x16x32_bf16(af[mb], bf, acc[mb][nb], 0, 0, 0);
;     ...
;     const float bd = __expf(tot);
; #pragma unroll
;     for (int mb = 0; mb < 4; ++mb)
; #pragma unroll
;       for (int nb = 0; nb < 8; ++nb)
; #pragma unroll
;         for (int j = 0; j < 4; ++j) {
;           const int o = (mb * 16 + (lane >> 4) * 4 + j) * 128 + nb * 16 + (lane & 15);
;           dst[o] = h0[o] * bd + acc[mb][nb][j];
	v_fma_f32 v72, v85, v72, v73
	global_load_dword v78, v[78:79], off
	global_store_dword v[76:77], v72, off
	v_or_b32_e32 v76, v106, v87
	v_lshl_add_u64 v[72:73], v[80:81], 0, v[2:3]
	v_lshlrev_b32_e32 v2, 2, v76
	v_lshl_add_u64 v[76:77], v[0:1], 0, v[2:3]
	s_waitcnt vmcnt(1)
	v_fma_f32 v74, v85, v78, v74
	global_store_dword v[72:73], v74, off
	global_load_dword v73, v[76:77], off
	v_or_b32_e32 v72, 0x1000, v86
	v_or_b32_e32 v74, v72, v84
	v_lshl_add_u64 v[76:77], v[80:81], 0, v[2:3]
	v_lshlrev_b32_e32 v2, 2, v74
	v_lshl_add_u64 v[78:79], v[0:1], 0, v[2:3]
	s_waitcnt vmcnt(0)
	v_fmac_f32_e32 v75, v85, v73
	global_load_dword v73, v[78:79], off
	global_store_dword v[76:77], v75, off
	ds_read_b64_tr_b16 v[74:75], v94 offset:17472
	ds_read_b64_tr_b16 v[76:77], v94 offset:18048
	ds_read_b64_tr_b16 v[96:97], v94 offset:22080
	ds_read_b64_tr_b16 v[98:99], v94 offset:22656
	s_waitcnt lgkmcnt(2)
	v_mfma_f32_16x16x32_bf16 v[100:103], v[74:77], v[68:71], 0
	v_lshl_add_u64 v[78:79], v[80:81], 0, v[2:3]
	v_lshlrev_b32_e32 v2, 2, v82
	v_lshl_add_u64 v[82:83], v[0:1], 0, v[2:3]
	s_waitcnt lgkmcnt(0)
	v_mfma_f32_16x16x32_bf16 v[100:103], v[96:99], v[8:11], v[100:103]
	v_mfma_f32_16x16x32_bf16 v[104:107], v[74:77], v[40:43], 0
	s_waitcnt vmcnt(1)
	s_nop 5
	v_fma_f32 v73, v85, v73, v100
	global_load_dword v73, v[82:83], off
	global_store_dword v[78:79], v73, off
	v_or_b32_e32 v82, v108, v84
	v_lshl_add_u64 v[78:79], v[80:81], 0, v[2:3]
	v_lshlrev_b32_e32 v2, 2, v82
	v_lshl_add_u64 v[82:83], v[0:1], 0, v[2:3]
	s_waitcnt vmcnt(1)
	v_fma_f32 v73, v85, v73, v101
	global_load_dword v73, v[82:83], off
	global_store_dword v[78:79], v73, off
	v_or_b32_e32 v82, v109, v84
	v_lshl_add_u64 v[78:79], v[80:81], 0, v[2:3]
	v_lshlrev_b32_e32 v2, 2, v82
	v_lshl_add_u64 v[82:83], v[0:1], 0, v[2:3]
	s_waitcnt vmcnt(1)
	v_fma_f32 v73, v85, v73, v102
	global_load_dword v73, v[82:83], off
	global_store_dword v[78:79], v73, off
	v_or_b32_e32 v82, v72, v90
	v_lshl_add_u64 v[78:79], v[80:81], 0, v[2:3]
	v_lshlrev_b32_e32 v2, 2, v82
	v_lshl_add_u64 v[82:83], v[0:1], 0, v[2:3]
	s_waitcnt vmcnt(1)
	v_fmac_f32_e32 v103, v85, v73
	global_load_dword v73, v[82:83], off
	global_store_dword v[78:79], v103, off
	v_mfma_f32_16x16x32_bf16 v[100:103], v[96:99], v[32:35], v[104:107]
	v_or_b32_e32 v82, v95, v90
	v_lshl_add_u64 v[78:79], v[80:81], 0, v[2:3]
	v_lshlrev_b32_e32 v2, 2, v82
	v_lshl_add_u64 v[82:83], v[0:1], 0, v[2:3]
	v_mfma_f32_16x16x32_bf16 v[104:107], v[74:77], v[52:55], 0
	s_waitcnt vmcnt(1)
	s_nop 1
	v_fma_f32 v73, v85, v73, v100
	global_load_dword v73, v[82:83], off
	global_store_dword v[78:79], v73, off
	v_or_b32_e32 v82, v108, v90
	v_lshl_add_u64 v[78:79], v[80:81], 0, v[2:3]
	v_lshlrev_b32_e32 v2, 2, v82
	v_lshl_add_u64 v[82:83], v[0:1], 0, v[2:3]
	s_waitcnt vmcnt(1)
	v_fma_f32 v73, v85, v73, v101
	global_load_dword v73, v[82:83], off
	global_store_dword v[78:79], v73, off
	v_or_b32_e32 v82, v109, v90
	v_lshl_add_u64 v[78:79], v[80:81], 0, v[2:3]
	v_lshlrev_b32_e32 v2, 2, v82
	v_lshl_add_u64 v[82:83], v[0:1], 0, v[2:3]
	s_waitcnt vmcnt(1)
	v_fma_f32 v73, v85, v73, v102
	global_load_dword v73, v[82:83], off
	global_store_dword v[78:79], v73, off
	v_or_b32_e32 v82, v72, v91
	v_lshl_add_u64 v[78:79], v[80:81], 0, v[2:3]
	v_lshlrev_b32_e32 v2, 2, v82
	v_lshl_add_u64 v[82:83], v[0:1], 0, v[2:3]
	s_waitcnt vmcnt(1)
	v_fmac_f32_e32 v103, v85, v73
	global_load_dword v73, v[82:83], off
	global_store_dword v[78:79], v103, off
	v_mfma_f32_16x16x32_bf16 v[100:103], v[96:99], v[44:47], v[104:107]
	v_or_b32_e32 v82, v95, v91
	v_lshl_add_u64 v[78:79], v[80:81], 0, v[2:3]
	v_lshlrev_b32_e32 v2, 2, v82
	v_lshl_add_u64 v[82:83], v[0:1], 0, v[2:3]
	v_mfma_f32_16x16x32_bf16 v[104:107], v[74:77], v[64:67], 0
	s_waitcnt vmcnt(1)
	s_nop 1
	v_fma_f32 v73, v85, v73, v100
	global_load_dword v73, v[82:83], off
	global_store_dword v[78:79], v73, off
	v_or_b32_e32 v82, v108, v91
	v_lshl_add_u64 v[78:79], v[80:81], 0, v[2:3]
	v_lshlrev_b32_e32 v2, 2, v82
	v_lshl_add_u64 v[82:83], v[0:1], 0, v[2:3]
	s_waitcnt vmcnt(1)
	v_fma_f32 v73, v85, v73, v101
	global_load_dword v73, v[82:83], off
	global_store_dword v[78:79], v73, off
	v_or_b32_e32 v82, v109, v91
	v_lshl_add_u64 v[78:79], v[80:81], 0, v[2:3]
	v_lshlrev_b32_e32 v2, 2, v82
	v_lshl_add_u64 v[82:83], v[0:1], 0, v[2:3]
	s_waitcnt vmcnt(1)
	v_fma_f32 v73, v85, v73, v102
	global_load_dword v73, v[82:83], off
	global_store_dword v[78:79], v73, off
	v_or_b32_e32 v82, v72, v93
	v_lshl_add_u64 v[78:79], v[80:81], 0, v[2:3]
	v_lshlrev_b32_e32 v2, 2, v82
	v_lshl_add_u64 v[82:83], v[0:1], 0, v[2:3]
	s_waitcnt vmcnt(1)
	v_fmac_f32_e32 v103, v85, v73
	global_load_dword v73, v[82:83], off
	global_store_dword v[78:79], v103, off
	v_mfma_f32_16x16x32_bf16 v[100:103], v[96:99], v[60:63], v[104:107]
	v_or_b32_e32 v82, v95, v93
	v_lshl_add_u64 v[78:79], v[80:81], 0, v[2:3]
	v_lshlrev_b32_e32 v2, 2, v82
	v_lshl_add_u64 v[82:83], v[0:1], 0, v[2:3]
	v_mfma_f32_16x16x32_bf16 v[104:107], v[74:77], v[56:59], 0
	s_waitcnt vmcnt(1)
	s_nop 1
	v_fma_f32 v73, v85, v73, v100
	global_load_dword v73, v[82:83], off
	global_store_dword v[78:79], v73, off
	v_or_b32_e32 v82, v108, v93
	v_lshl_add_u64 v[78:79], v[80:81], 0, v[2:3]
	v_lshlrev_b32_e32 v2, 2, v82
	v_lshl_add_u64 v[82:83], v[0:1], 0, v[2:3]
	s_waitcnt vmcnt(1)
	v_fma_f32 v73, v85, v73, v101
	global_load_dword v73, v[82:83], off
	global_store_dword v[78:79], v73, off
	v_or_b32_e32 v82, v109, v93
	v_lshl_add_u64 v[78:79], v[80:81], 0, v[2:3]
	v_lshlrev_b32_e32 v2, 2, v82
	v_lshl_add_u64 v[82:83], v[0:1], 0, v[2:3]
	s_waitcnt vmcnt(1)
; __device__ __forceinline__ bf16x8 cat44(s16x4 a, s16x4 b) { return (bf16x8){a[0], a[1], a[2], a[3], b[0], b[1], b[2], b[3]}; }
; __device__ __forceinline__ void ssd_states_item(KP P, int l, int seq, int c, int g, char* smem) {
;     ...
;     for (int nb = 0; nb < 8; ++nb) {
;       const u16* p0 = Bs + (ks * 32 + trr) * 136 + nb * 16 + trc;
;       const bf16x8 bf = cat44(ldtr(p0), ldtr(p0 + 4 * 136));
; #pragma unroll
;       for (int mb = 0; mb < 4; ++mb) acc[mb][nb] = __builtin_amdgcn_mfma_f32_16x16x32_bf16(af[mb], bf, acc[mb][nb], 0, 0, 0);
;     ...
;     const float bd = __expf(tot);
; #pragma unroll
;     for (int mb = 0; mb < 4; ++mb)
; #pragma unroll
;       for (int nb = 0; nb < 8; ++nb)
; #pragma unroll
;         for (int j = 0; j < 4; ++j) {
;           const int o = (mb * 16 + (lane >> 4) * 4 + j) * 128 + nb * 16 + (lane & 15);
;           dst[o] = h0[o] * bd + acc[mb][nb][j];
	v_fma_f32 v73, v85, v73, v102
	global_load_dword v73, v[82:83], off
	global_store_dword v[78:79], v73, off
	v_or_b32_e32 v82, v72, v92
	v_lshl_add_u64 v[78:79], v[80:81], 0, v[2:3]
	v_lshlrev_b32_e32 v2, 2, v82
	v_lshl_add_u64 v[82:83], v[0:1], 0, v[2:3]
	s_waitcnt vmcnt(1)
	v_fmac_f32_e32 v103, v85, v73
	global_load_dword v73, v[82:83], off
	global_store_dword v[78:79], v103, off
	v_mfma_f32_16x16x32_bf16 v[100:103], v[96:99], v[48:51], v[104:107]
	v_or_b32_e32 v82, v95, v92
	v_lshl_add_u64 v[78:79], v[80:81], 0, v[2:3]
	v_lshlrev_b32_e32 v2, 2, v82
	v_lshl_add_u64 v[82:83], v[0:1], 0, v[2:3]
	v_mfma_f32_16x16x32_bf16 v[104:107], v[74:77], v[36:39], 0
	s_waitcnt vmcnt(1)
	s_nop 1
	v_fma_f32 v73, v85, v73, v100
	global_load_dword v73, v[82:83], off
	global_store_dword v[78:79], v73, off
	v_or_b32_e32 v82, v108, v92
	v_lshl_add_u64 v[78:79], v[80:81], 0, v[2:3]
	v_lshlrev_b32_e32 v2, 2, v82
	v_lshl_add_u64 v[82:83], v[0:1], 0, v[2:3]
	s_waitcnt vmcnt(1)
	v_fma_f32 v73, v85, v73, v101
	global_load_dword v73, v[82:83], off
	global_store_dword v[78:79], v73, off
	v_or_b32_e32 v82, v109, v92
	v_lshl_add_u64 v[78:79], v[80:81], 0, v[2:3]
	v_lshlrev_b32_e32 v2, 2, v82
	v_lshl_add_u64 v[82:83], v[0:1], 0, v[2:3]
	s_waitcnt vmcnt(1)
	v_fma_f32 v73, v85, v73, v102
	global_load_dword v73, v[82:83], off
	global_store_dword v[78:79], v73, off
	v_or_b32_e32 v82, v72, v89
	v_lshl_add_u64 v[78:79], v[80:81], 0, v[2:3]
	v_lshlrev_b32_e32 v2, 2, v82
	v_lshl_add_u64 v[82:83], v[0:1], 0, v[2:3]
	s_waitcnt vmcnt(1)
	v_fmac_f32_e32 v103, v85, v73
	global_load_dword v73, v[82:83], off
	global_store_dword v[78:79], v103, off
	v_mfma_f32_16x16x32_bf16 v[100:103], v[96:99], v[28:31], v[104:107]
	v_or_b32_e32 v82, v95, v89
	v_lshl_add_u64 v[78:79], v[80:81], 0, v[2:3]
	v_lshlrev_b32_e32 v2, 2, v82
	v_lshl_add_u64 v[82:83], v[0:1], 0, v[2:3]
	v_mfma_f32_16x16x32_bf16 v[104:107], v[74:77], v[24:27], 0
	s_waitcnt vmcnt(1)
	s_nop 1
	v_fma_f32 v73, v85, v73, v100
	global_load_dword v73, v[82:83], off
	global_store_dword v[78:79], v73, off
	v_or_b32_e32 v82, v108, v89
	v_lshl_add_u64 v[78:79], v[80:81], 0, v[2:3]
	v_lshlrev_b32_e32 v2, 2, v82
	v_lshl_add_u64 v[82:83], v[0:1], 0, v[2:3]
	s_waitcnt vmcnt(1)
	v_fma_f32 v73, v85, v73, v101
	global_load_dword v73, v[82:83], off
	global_store_dword v[78:79], v73, off
	v_or_b32_e32 v82, v109, v89
	v_lshl_add_u64 v[78:79], v[80:81], 0, v[2:3]
	v_lshlrev_b32_e32 v2, 2, v82
	v_lshl_add_u64 v[82:83], v[0:1], 0, v[2:3]
	s_waitcnt vmcnt(1)
	v_fma_f32 v73, v85, v73, v102
	global_load_dword v73, v[82:83], off
	global_store_dword v[78:79], v73, off
	v_or_b32_e32 v82, v72, v88
	v_lshl_add_u64 v[78:79], v[80:81], 0, v[2:3]
	v_lshlrev_b32_e32 v2, 2, v82
	v_lshl_add_u64 v[82:83], v[0:1], 0, v[2:3]
	s_waitcnt vmcnt(1)
	v_fmac_f32_e32 v103, v85, v73
	global_load_dword v73, v[82:83], off
	global_store_dword v[78:79], v103, off
	v_mfma_f32_16x16x32_bf16 v[100:103], v[96:99], v[20:23], v[104:107]
	v_or_b32_e32 v82, v95, v88
	v_lshl_add_u64 v[78:79], v[80:81], 0, v[2:3]
	v_lshlrev_b32_e32 v2, 2, v82
	v_lshl_add_u64 v[82:83], v[0:1], 0, v[2:3]
	s_waitcnt vmcnt(1)
	s_nop 2
	v_fma_f32 v73, v85, v73, v100
	global_load_dword v73, v[82:83], off
	global_store_dword v[78:79], v73, off
	v_or_b32_e32 v82, v108, v88
	v_lshl_add_u64 v[78:79], v[80:81], 0, v[2:3]
	v_lshlrev_b32_e32 v2, 2, v82
	v_lshl_add_u64 v[82:83], v[0:1], 0, v[2:3]
	s_waitcnt vmcnt(1)
	v_fma_f32 v73, v85, v73, v101
	global_load_dword v73, v[82:83], off
	global_store_dword v[78:79], v73, off
	v_or_b32_e32 v82, v109, v88
	v_lshl_add_u64 v[78:79], v[80:81], 0, v[2:3]
	v_lshlrev_b32_e32 v2, 2, v82
	v_lshl_add_u64 v[82:83], v[0:1], 0, v[2:3]
	s_waitcnt vmcnt(1)
	v_fma_f32 v73, v85, v73, v102
	global_load_dword v82, v[82:83], off
	global_store_dword v[78:79], v73, off
	v_or_b32_e32 v78, v72, v87
	v_mfma_f32_16x16x32_bf16 v[72:75], v[74:77], v[16:19], 0
	v_lshl_add_u64 v[76:77], v[80:81], 0, v[2:3]
	v_lshlrev_b32_e32 v2, 2, v78
	v_lshl_add_u64 v[78:79], v[0:1], 0, v[2:3]
	v_mfma_f32_16x16x32_bf16 v[72:75], v[96:99], v[12:15], v[72:75]
	s_waitcnt vmcnt(1)
	v_fmac_f32_e32 v103, v85, v82
	global_load_dword v82, v[78:79], off
	global_store_dword v[76:77], v103, off
	v_or_b32_e32 v78, v95, v87
	v_lshl_add_u64 v[76:77], v[80:81], 0, v[2:3]
	v_lshlrev_b32_e32 v2, 2, v78
	v_lshl_add_u64 v[78:79], v[0:1], 0, v[2:3]
	s_waitcnt vmcnt(1)
	v_fma_f32 v72, v85, v82, v72
	global_load_dword v72, v[78:79], off
	global_store_dword v[76:77], v72, off
	v_or_b32_e32 v78, v108, v87
	v_lshl_add_u64 v[76:77], v[80:81], 0, v[2:3]
	v_lshlrev_b32_e32 v2, 2, v78
	v_lshl_add_u64 v[78:79], v[0:1], 0, v[2:3]
	v_or_b32_e32 v82, 0x1800, v86
	s_waitcnt vmcnt(1)
	v_fma_f32 v72, v85, v72, v73
	global_load_dword v78, v[78:79], off
	global_store_dword v[76:77], v72, off
	v_or_b32_e32 v76, v109, v87
	v_lshl_add_u64 v[72:73], v[80:81], 0, v[2:3]
	v_lshlrev_b32_e32 v2, 2, v76
	v_lshl_add_u64 v[76:77], v[0:1], 0, v[2:3]
	s_waitcnt vmcnt(1)
	v_fma_f32 v74, v85, v78, v74
	global_load_dword v74, v[76:77], off
	global_store_dword v[72:73], v74, off
	v_or_b32_e32 v76, v82, v84
	v_lshl_add_u64 v[72:73], v[80:81], 0, v[2:3]
	v_lshlrev_b32_e32 v2, 2, v76
	v_lshl_add_u64 v[76:77], v[0:1], 0, v[2:3]
	s_waitcnt vmcnt(1)
	v_fmac_f32_e32 v75, v85, v74
	global_load_dword v83, v[76:77], off
	global_store_dword v[72:73], v75, off
	ds_read_b64_tr_b16 v[72:73], v94 offset:17504
	ds_read_b64_tr_b16 v[74:75], v94 offset:18080
	ds_read_b64_tr_b16 v[76:77], v94 offset:22112
	ds_read_b64_tr_b16 v[78:79], v94 offset:22688
	s_waitcnt lgkmcnt(2)
	v_mfma_f32_16x16x32_bf16 v[68:71], v[72:75], v[68:71], 0
	v_or_b32_e32 v94, 0x1880, v86
	v_or_b32_e32 v95, v94, v84
	s_waitcnt lgkmcnt(0)
; __device__ __forceinline__ bf16x8 cat44(s16x4 a, s16x4 b) { return (bf16x8){a[0], a[1], a[2], a[3], b[0], b[1], b[2], b[3]}; }
; __device__ __forceinline__ void ssd_states_item(KP P, int l, int seq, int c, int g, char* smem) {
;     ...
;     for (int nb = 0; nb < 8; ++nb) {
;       const u16* p0 = Bs + (ks * 32 + trr) * 136 + nb * 16 + trc;
;       const bf16x8 bf = cat44(ldtr(p0), ldtr(p0 + 4 * 136));
; #pragma unroll
;       for (int mb = 0; mb < 4; ++mb) acc[mb][nb] = __builtin_amdgcn_mfma_f32_16x16x32_bf16(af[mb], bf, acc[mb][nb], 0, 0, 0);
;     ...
;     const float bd = __expf(tot);
; #pragma unroll
;     for (int mb = 0; mb < 4; ++mb)
; #pragma unroll
;       for (int nb = 0; nb < 8; ++nb)
; #pragma unroll
;         for (int j = 0; j < 4; ++j) {
;           const int o = (mb * 16 + (lane >> 4) * 4 + j) * 128 + nb * 16 + (lane & 15);
;           dst[o] = h0[o] * bd + acc[mb][nb][j];
	v_mfma_f32_16x16x32_bf16 v[8:11], v[76:79], v[8:11], v[68:71]
	s_nop 3
	v_lshl_add_u64 v[68:69], v[80:81], 0, v[2:3]
	v_lshlrev_b32_e32 v2, 2, v95
	v_lshl_add_u64 v[70:71], v[0:1], 0, v[2:3]
	v_mfma_f32_16x16x32_bf16 v[40:43], v[72:75], v[40:43], 0
	s_waitcnt vmcnt(1)
	v_fma_f32 v8, v85, v83, v8
	global_load_dword v8, v[70:71], off
	global_store_dword v[68:69], v8, off
	v_or_b32_e32 v83, 0x1900, v86
	v_or_b32_e32 v70, v83, v84
	v_lshl_add_u64 v[68:69], v[80:81], 0, v[2:3]
	v_lshlrev_b32_e32 v2, 2, v70
	v_lshl_add_u64 v[70:71], v[0:1], 0, v[2:3]
	v_mfma_f32_16x16x32_bf16 v[24:27], v[72:75], v[24:27], 0
	s_waitcnt vmcnt(1)
	v_fma_f32 v8, v85, v8, v9
	global_load_dword v70, v[70:71], off
	global_store_dword v[68:69], v8, off
	v_or_b32_e32 v71, 0x1980, v86
	v_or_b32_e32 v68, v71, v84
	v_lshl_add_u64 v[8:9], v[80:81], 0, v[2:3]
	v_lshlrev_b32_e32 v2, 2, v68
	v_lshl_add_u64 v[68:69], v[0:1], 0, v[2:3]
	v_mfma_f32_16x16x32_bf16 v[16:19], v[72:75], v[16:19], 0
	s_waitcnt vmcnt(1)
	v_fma_f32 v10, v85, v70, v10
	global_load_dword v10, v[68:69], off
	global_store_dword v[8:9], v10, off
	v_or_b32_e32 v68, v82, v90
	v_lshl_add_u64 v[8:9], v[80:81], 0, v[2:3]
	v_lshlrev_b32_e32 v2, 2, v68
	v_lshl_add_u64 v[68:69], v[0:1], 0, v[2:3]
	s_waitcnt vmcnt(1)
	v_fmac_f32_e32 v11, v85, v10
	global_load_dword v68, v[68:69], off
	global_store_dword v[8:9], v11, off
	v_mfma_f32_16x16x32_bf16 v[8:11], v[76:79], v[32:35], v[40:43]
	v_or_b32_e32 v69, v94, v90
	v_lshl_add_u64 v[32:33], v[80:81], 0, v[2:3]
	v_lshlrev_b32_e32 v2, 2, v69
	v_lshl_add_u64 v[34:35], v[0:1], 0, v[2:3]
	v_or_b32_e32 v40, v82, v91
	s_waitcnt vmcnt(1)
	s_nop 1
	v_fma_f32 v8, v85, v68, v8
	global_load_dword v8, v[34:35], off
	global_store_dword v[32:33], v8, off
	v_or_b32_e32 v34, v83, v90
	v_lshl_add_u64 v[32:33], v[80:81], 0, v[2:3]
	v_lshlrev_b32_e32 v2, 2, v34
	v_lshl_add_u64 v[34:35], v[0:1], 0, v[2:3]
	s_waitcnt vmcnt(1)
	v_fma_f32 v8, v85, v8, v9
	global_load_dword v34, v[34:35], off
	global_store_dword v[32:33], v8, off
	v_or_b32_e32 v32, v71, v90
	v_lshl_add_u64 v[8:9], v[80:81], 0, v[2:3]
	v_lshlrev_b32_e32 v2, 2, v32
	v_lshl_add_u64 v[32:33], v[0:1], 0, v[2:3]
	s_waitcnt vmcnt(1)
	v_fma_f32 v10, v85, v34, v10
	global_load_dword v10, v[32:33], off
	global_store_dword v[8:9], v10, off
	v_lshl_add_u64 v[8:9], v[80:81], 0, v[2:3]
	v_lshlrev_b32_e32 v2, 2, v40
	v_lshl_add_u64 v[40:41], v[0:1], 0, v[2:3]
	v_mfma_f32_16x16x32_bf16 v[32:35], v[72:75], v[52:55], 0
	s_waitcnt vmcnt(1)
	v_fmac_f32_e32 v11, v85, v10
	global_load_dword v40, v[40:41], off
	global_store_dword v[8:9], v11, off
	v_mfma_f32_16x16x32_bf16 v[8:11], v[76:79], v[44:47], v[32:35]
	v_or_b32_e32 v41, v94, v91
	s_nop 1
	v_lshl_add_u64 v[32:33], v[80:81], 0, v[2:3]
	v_lshlrev_b32_e32 v2, 2, v41
	v_lshl_add_u64 v[34:35], v[0:1], 0, v[2:3]
	s_waitcnt vmcnt(1)
	s_nop 0
	v_fma_f32 v8, v85, v40, v8
	global_load_dword v8, v[34:35], off
	global_store_dword v[32:33], v8, off
	v_or_b32_e32 v34, v83, v91
	v_lshl_add_u64 v[32:33], v[80:81], 0, v[2:3]
	v_lshlrev_b32_e32 v2, 2, v34
	v_lshl_add_u64 v[34:35], v[0:1], 0, v[2:3]
	v_or_b32_e32 v40, v82, v93
	s_waitcnt vmcnt(1)
	v_fma_f32 v8, v85, v8, v9
	global_load_dword v34, v[34:35], off
	global_store_dword v[32:33], v8, off
	v_or_b32_e32 v32, v71, v91
	v_lshl_add_u64 v[8:9], v[80:81], 0, v[2:3]
	v_lshlrev_b32_e32 v2, 2, v32
	v_lshl_add_u64 v[32:33], v[0:1], 0, v[2:3]
	s_waitcnt vmcnt(1)
	v_fma_f32 v10, v85, v34, v10
	global_load_dword v10, v[32:33], off
	global_store_dword v[8:9], v10, off
	v_lshl_add_u64 v[8:9], v[80:81], 0, v[2:3]
	v_lshlrev_b32_e32 v2, 2, v40
	v_lshl_add_u64 v[40:41], v[0:1], 0, v[2:3]
	v_mfma_f32_16x16x32_bf16 v[32:35], v[72:75], v[64:67], 0
	s_waitcnt vmcnt(1)
	v_fmac_f32_e32 v11, v85, v10
	global_load_dword v40, v[40:41], off
	global_store_dword v[8:9], v11, off
	v_mfma_f32_16x16x32_bf16 v[8:11], v[76:79], v[60:63], v[32:35]
	v_or_b32_e32 v41, v94, v93
	s_nop 1
	v_lshl_add_u64 v[32:33], v[80:81], 0, v[2:3]
	v_lshlrev_b32_e32 v2, 2, v41
	v_lshl_add_u64 v[34:35], v[0:1], 0, v[2:3]
	s_waitcnt vmcnt(1)
	s_nop 0
	v_fma_f32 v8, v85, v40, v8
	global_load_dword v8, v[34:35], off
	global_store_dword v[32:33], v8, off
	v_or_b32_e32 v34, v83, v93
	v_lshl_add_u64 v[32:33], v[80:81], 0, v[2:3]
	v_lshlrev_b32_e32 v2, 2, v34
	v_lshl_add_u64 v[34:35], v[0:1], 0, v[2:3]
	v_or_b32_e32 v40, v82, v92
	s_waitcnt vmcnt(1)
	v_fma_f32 v8, v85, v8, v9
	global_load_dword v34, v[34:35], off
	global_store_dword v[32:33], v8, off
	v_or_b32_e32 v32, v71, v93
	v_lshl_add_u64 v[8:9], v[80:81], 0, v[2:3]
	v_lshlrev_b32_e32 v2, 2, v32
	v_lshl_add_u64 v[32:33], v[0:1], 0, v[2:3]
	s_waitcnt vmcnt(1)
	v_fma_f32 v10, v85, v34, v10
	global_load_dword v10, v[32:33], off
	global_store_dword v[8:9], v10, off
	v_lshl_add_u64 v[8:9], v[80:81], 0, v[2:3]
	v_lshlrev_b32_e32 v2, 2, v40
	v_lshl_add_u64 v[40:41], v[0:1], 0, v[2:3]
	v_mfma_f32_16x16x32_bf16 v[32:35], v[72:75], v[56:59], 0
	s_waitcnt vmcnt(1)
; __device__ __forceinline__ void ssd_states_item(KP P, int l, int seq, int c, int g, char* smem) {
;     ...
;     const float bd = __expf(tot);
; #pragma unroll
;     for (int mb = 0; mb < 4; ++mb)
; #pragma unroll
;       for (int nb = 0; nb < 8; ++nb)
; #pragma unroll
;         for (int j = 0; j < 4; ++j) {
;           const int o = (mb * 16 + (lane >> 4) * 4 + j) * 128 + nb * 16 + (lane & 15);
;           dst[o] = h0[o] * bd + acc[mb][nb][j];
;         }
;   }
;   __syncthreads();
	v_fmac_f32_e32 v11, v85, v10
	global_load_dword v40, v[40:41], off
	global_store_dword v[8:9], v11, off
	v_mfma_f32_16x16x32_bf16 v[8:11], v[76:79], v[48:51], v[32:35]
	v_or_b32_e32 v41, v94, v92
	s_nop 1
	v_lshl_add_u64 v[32:33], v[80:81], 0, v[2:3]
	v_lshlrev_b32_e32 v2, 2, v41
	v_lshl_add_u64 v[34:35], v[0:1], 0, v[2:3]
	s_waitcnt vmcnt(1)
	s_nop 0
	v_fma_f32 v8, v85, v40, v8
	global_load_dword v8, v[34:35], off
	global_store_dword v[32:33], v8, off
	v_or_b32_e32 v34, v83, v92
	v_lshl_add_u64 v[32:33], v[80:81], 0, v[2:3]
	v_lshlrev_b32_e32 v2, 2, v34
	v_lshl_add_u64 v[34:35], v[0:1], 0, v[2:3]
	v_or_b32_e32 v40, v82, v89
	s_waitcnt vmcnt(1)
	v_fma_f32 v8, v85, v8, v9
	global_load_dword v34, v[34:35], off
	global_store_dword v[32:33], v8, off
	v_or_b32_e32 v32, v71, v92
	v_lshl_add_u64 v[8:9], v[80:81], 0, v[2:3]
	v_lshlrev_b32_e32 v2, 2, v32
	v_lshl_add_u64 v[32:33], v[0:1], 0, v[2:3]
	s_waitcnt vmcnt(1)
	v_fma_f32 v10, v85, v34, v10
	global_load_dword v10, v[32:33], off
	global_store_dword v[8:9], v10, off
	v_lshl_add_u64 v[8:9], v[80:81], 0, v[2:3]
	v_lshlrev_b32_e32 v2, 2, v40
	v_mfma_f32_16x16x32_bf16 v[32:35], v[72:75], v[36:39], 0
	v_lshl_add_u64 v[36:37], v[0:1], 0, v[2:3]
	s_waitcnt vmcnt(1)
	v_fmac_f32_e32 v11, v85, v10
	global_load_dword v36, v[36:37], off
	global_store_dword v[8:9], v11, off
	v_mfma_f32_16x16x32_bf16 v[8:11], v[76:79], v[28:31], v[32:35]
	v_or_b32_e32 v37, v94, v89
	v_lshl_add_u64 v[28:29], v[80:81], 0, v[2:3]
	v_lshlrev_b32_e32 v2, 2, v37
	v_lshl_add_u64 v[30:31], v[0:1], 0, v[2:3]
	s_waitcnt vmcnt(1)
	s_nop 2
	v_fma_f32 v8, v85, v36, v8
	global_load_dword v8, v[30:31], off
	global_store_dword v[28:29], v8, off
	v_or_b32_e32 v30, v83, v89
	v_lshl_add_u64 v[28:29], v[80:81], 0, v[2:3]
	v_lshlrev_b32_e32 v2, 2, v30
	v_lshl_add_u64 v[30:31], v[0:1], 0, v[2:3]
	s_waitcnt vmcnt(1)
	v_fma_f32 v8, v85, v8, v9
	global_load_dword v30, v[30:31], off
	global_store_dword v[28:29], v8, off
	v_or_b32_e32 v28, v71, v89
	v_lshl_add_u64 v[8:9], v[80:81], 0, v[2:3]
	v_lshlrev_b32_e32 v2, 2, v28
	v_lshl_add_u64 v[28:29], v[0:1], 0, v[2:3]
	s_waitcnt vmcnt(1)
	v_fma_f32 v10, v85, v30, v10
	global_load_dword v10, v[28:29], off
	global_store_dword v[8:9], v10, off
	v_or_b32_e32 v28, v82, v88
	v_lshl_add_u64 v[8:9], v[80:81], 0, v[2:3]
	v_lshlrev_b32_e32 v2, 2, v28
	v_lshl_add_u64 v[28:29], v[0:1], 0, v[2:3]
	s_waitcnt vmcnt(1)
	v_fmac_f32_e32 v11, v85, v10
	global_load_dword v28, v[28:29], off
	global_store_dword v[8:9], v11, off
	v_mfma_f32_16x16x32_bf16 v[8:11], v[76:79], v[20:23], v[24:27]
	v_or_b32_e32 v29, v94, v88
	v_lshl_add_u64 v[20:21], v[80:81], 0, v[2:3]
	v_lshlrev_b32_e32 v2, 2, v29
	v_lshl_add_u64 v[22:23], v[0:1], 0, v[2:3]
	s_waitcnt vmcnt(1)
	s_nop 2
	v_fma_f32 v8, v85, v28, v8
	global_load_dword v8, v[22:23], off
	global_store_dword v[20:21], v8, off
	v_or_b32_e32 v22, v83, v88
	v_lshl_add_u64 v[20:21], v[80:81], 0, v[2:3]
	v_lshlrev_b32_e32 v2, 2, v22
	v_lshl_add_u64 v[22:23], v[0:1], 0, v[2:3]
	s_waitcnt vmcnt(1)
	v_fma_f32 v8, v85, v8, v9
	global_load_dword v22, v[22:23], off
	global_store_dword v[20:21], v8, off
	v_or_b32_e32 v20, v71, v88
	v_lshl_add_u64 v[8:9], v[80:81], 0, v[2:3]
	v_lshlrev_b32_e32 v2, 2, v20
	v_lshl_add_u64 v[20:21], v[0:1], 0, v[2:3]
	s_waitcnt vmcnt(1)
	v_fma_f32 v10, v85, v22, v10
	global_load_dword v10, v[20:21], off
	global_store_dword v[8:9], v10, off
	v_or_b32_e32 v20, v82, v87
	v_lshl_add_u64 v[8:9], v[80:81], 0, v[2:3]
	v_lshlrev_b32_e32 v2, 2, v20
	v_lshl_add_u64 v[20:21], v[0:1], 0, v[2:3]
	s_waitcnt vmcnt(1)
	v_fmac_f32_e32 v11, v85, v10
	global_load_dword v20, v[20:21], off
	global_store_dword v[8:9], v11, off
	v_mfma_f32_16x16x32_bf16 v[8:11], v[76:79], v[12:15], v[16:19]
	v_or_b32_e32 v21, v94, v87
	v_lshl_add_u64 v[12:13], v[80:81], 0, v[2:3]
	v_lshlrev_b32_e32 v2, 2, v21
	v_lshl_add_u64 v[14:15], v[0:1], 0, v[2:3]
	s_waitcnt vmcnt(1)
	s_nop 2
	v_fma_f32 v8, v85, v20, v8
	global_load_dword v8, v[14:15], off
	global_store_dword v[12:13], v8, off
	v_or_b32_e32 v14, v83, v87
	v_lshl_add_u64 v[12:13], v[80:81], 0, v[2:3]
	v_lshlrev_b32_e32 v2, 2, v14
	v_lshl_add_u64 v[14:15], v[0:1], 0, v[2:3]
	s_waitcnt vmcnt(1)
	v_fma_f32 v8, v85, v8, v9
	global_store_dword v[12:13], v8, off
	global_load_dword v12, v[14:15], off
	v_or_b32_e32 v13, v71, v87
	v_lshl_add_u64 v[8:9], v[80:81], 0, v[2:3]
	v_lshlrev_b32_e32 v2, 2, v13
	v_lshl_add_u64 v[0:1], v[0:1], 0, v[2:3]
	s_waitcnt vmcnt(0)
	v_fma_f32 v10, v85, v12, v10
	global_store_dword v[8:9], v10, off
	global_load_dword v8, v[0:1], off
	v_lshl_add_u64 v[0:1], v[80:81], 0, v[2:3]
	s_waitcnt vmcnt(0)
	v_fmac_f32_e32 v11, v85, v8
	global_store_dword v[0:1], v11, off
	s_barrier
